# lever 7: attention softmax row-max exchange across wave halves by v_permlane32_swap instead of ds_bpermute (one LDS round trip per KV block removed), on k49
# baseline (speedup 1.0000x reference)
.LBB0_768:
	v_mov_b32_e32 v51, v50
	v_pk_mul_f32 v[40:41], v[50:51], v[40:41]
	v_pk_mul_f32 v[38:39], v[50:51], v[38:39]
	v_pk_mul_f32 v[36:37], v[50:51], v[36:37]
	v_pk_mul_f32 v[34:35], v[50:51], v[34:35]
	v_pk_mul_f32 v[32:33], v[50:51], v[32:33]
	v_pk_mul_f32 v[30:31], v[50:51], v[30:31]
	v_pk_mul_f32 v[28:29], v[50:51], v[28:29]
	v_pk_mul_f32 v[26:27], v[50:51], v[26:27]
	v_pk_mul_f32 v[24:25], v[50:51], v[24:25]
	v_pk_mul_f32 v[22:23], v[50:51], v[22:23]
	v_pk_mul_f32 v[20:21], v[50:51], v[20:21]
	v_pk_mul_f32 v[18:19], v[50:51], v[18:19]
	s_waitcnt lgkmcnt(7)
	v_cndmask_b32_e64 v50, v58, -v58, s[4:5]
	s_waitcnt lgkmcnt(6)
	v_cndmask_b32_e64 v51, v59, -v59, s[4:5]
	s_waitcnt vmcnt(19)
	v_pk_mul_f32 v[14:15], v[14:15], v[50:51]
	v_pk_mul_f32 v[40:41], v[106:107], v[40:41]
	s_waitcnt vmcnt(17)
	v_pk_fma_f32 v[10:11], v[10:11], v[48:49], v[14:15]
	s_waitcnt lgkmcnt(5)
	v_cndmask_b32_e64 v14, v56, -v56, s[4:5]
	s_waitcnt lgkmcnt(4)
	v_cndmask_b32_e64 v15, v57, -v57, s[4:5]
	v_pk_mul_f32 v[14:15], v[16:17], v[14:15]
	v_pk_mul_f32 v[38:39], v[108:109], v[38:39]
	v_pk_fma_f32 v[12:13], v[12:13], v[46:47], v[14:15]
	s_waitcnt lgkmcnt(3)
	v_cndmask_b32_e64 v14, v54, -v54, s[4:5]
	s_waitcnt lgkmcnt(2)
	v_cndmask_b32_e64 v15, v55, -v55, s[4:5]
	v_pk_mul_f32 v[6:7], v[6:7], v[14:15]
	v_pk_mul_f32 v[36:37], v[110:111], v[36:37]
	v_pk_fma_f32 v[6:7], v[2:3], v[44:45], v[6:7]
	s_waitcnt lgkmcnt(1)
	v_cndmask_b32_e64 v2, v52, -v52, s[4:5]
	s_waitcnt lgkmcnt(0)
	v_cndmask_b32_e64 v3, v53, -v53, s[4:5]
	v_pk_mul_f32 v[2:3], v[8:9], v[2:3]
	v_pk_mul_f32 v[34:35], v[112:113], v[34:35]
	v_pk_fma_f32 v[8:9], v[4:5], v[42:43], v[2:3]
	v_pk_mul_f32 v[2:3], v[10:11], s[22:23] op_sel_hi:[1,0]
	v_pk_mul_f32 v[4:5], v[12:13], s[22:23] op_sel_hi:[1,0]
	v_cvt_pk_bf16_f32 v2, v2, v3
	v_cvt_pk_bf16_f32 v3, v4, v5
	v_pk_mul_f32 v[4:5], v[6:7], s[22:23] op_sel_hi:[1,0]
	v_pk_mul_f32 v[6:7], v[8:9], s[22:23] op_sel_hi:[1,0]
	v_cvt_pk_bf16_f32 v4, v4, v5
	v_cvt_pk_bf16_f32 v5, v6, v7
	v_pk_mul_f32 v[6:7], v[40:41], s[22:23] op_sel_hi:[1,0]
	v_pk_mul_f32 v[32:33], v[114:115], v[32:33]
	v_cvt_pk_bf16_f32 v146, v6, v7
	v_pk_mul_f32 v[6:7], v[38:39], s[22:23] op_sel_hi:[1,0]
	v_pk_mul_f32 v[30:31], v[116:117], v[30:31]
	v_cvt_pk_bf16_f32 v147, v6, v7
	v_pk_mul_f32 v[6:7], v[36:37], s[22:23] op_sel_hi:[1,0]
	v_pk_mul_f32 v[28:29], v[118:119], v[28:29]
	v_cvt_pk_bf16_f32 v148, v6, v7
	v_pk_mul_f32 v[6:7], v[34:35], s[22:23] op_sel_hi:[1,0]
	v_pk_mul_f32 v[26:27], v[120:121], v[26:27]
	v_cvt_pk_bf16_f32 v149, v6, v7
	v_pk_mul_f32 v[6:7], v[32:33], s[22:23] op_sel_hi:[1,0]
	v_pk_mul_f32 v[24:25], v[122:123], v[24:25]
	v_cvt_pk_bf16_f32 v150, v6, v7
	v_pk_mul_f32 v[6:7], v[30:31], s[22:23] op_sel_hi:[1,0]
	v_pk_mul_f32 v[22:23], v[124:125], v[22:23]
	v_cvt_pk_bf16_f32 v151, v6, v7
	v_pk_mul_f32 v[6:7], v[28:29], s[22:23] op_sel_hi:[1,0]
	v_pk_mul_f32 v[20:21], v[126:127], v[20:21]
	v_cvt_pk_bf16_f32 v152, v6, v7
	v_pk_mul_f32 v[6:7], v[26:27], s[22:23] op_sel_hi:[1,0]
	v_pk_mul_f32 v[18:19], v[128:129], v[18:19]
	v_cvt_pk_bf16_f32 v153, v6, v7
	v_pk_mul_f32 v[6:7], v[24:25], s[22:23] op_sel_hi:[1,0]
	s_lshl_b32 s29, s57, 12
	v_cvt_pk_bf16_f32 v154, v6, v7
	v_pk_mul_f32 v[6:7], v[22:23], s[22:23] op_sel_hi:[1,0]
	v_add_u32_e32 v10, s29, v202
	v_cvt_pk_bf16_f32 v155, v6, v7
	v_pk_mul_f32 v[6:7], v[20:21], s[22:23] op_sel_hi:[1,0]
	s_add_i32 s58, s57, 4
	v_cvt_pk_bf16_f32 v156, v6, v7
	v_pk_mul_f32 v[6:7], v[18:19], s[22:23] op_sel_hi:[1,0]
	s_lshl_b32 s56, s58, 12
	v_cvt_pk_bf16_f32 v157, v6, v7
	ds_read_b128 v[6:9], v10
	v_add_u32_e32 v175, s56, v202
	ds_read_b128 v[216:219], v175 offset:1024
	s_waitcnt lgkmcnt(1)
	v_mfma_f32_32x32x16_bf16 v[50:65], v[6:9], v[2:5], 0
	ds_read_b128 v[6:9], v10 offset:1024
	s_add_i32 s0, s57, 1
	s_lshl_b32 s51, s0, 12
	s_add_i32 s60, s57, 2
	s_lshl_b32 s52, s60, 12
	s_add_i32 s59, s57, 3
	s_lshl_b32 s53, s59, 12
	s_waitcnt lgkmcnt(0)
	v_mfma_f32_32x32x16_bf16 v[50:65], v[6:9], v[146:149], v[50:65]
	ds_read_b128 v[6:9], v10 offset:2048
	v_or_b32_e32 v231, 0x80, v215
	s_waitcnt lgkmcnt(0)
	v_mfma_f32_32x32x16_bf16 v[50:65], v[6:9], v[150:153], v[50:65]
	ds_read_b128 v[6:9], v10 offset:3072
	v_add_u32_e32 v10, s51, v202
	s_waitcnt lgkmcnt(0)
	v_mfma_f32_32x32x16_bf16 v[50:65], v[6:9], v[154:157], v[50:65]
	ds_read_b128 v[6:9], v10
	s_waitcnt lgkmcnt(0)
	v_mfma_f32_32x32x16_bf16 v[66:81], v[6:9], v[2:5], 0
	ds_read_b128 v[6:9], v10 offset:1024
	s_nop 7
	v_cndmask_b32_e64 v227, v210, v51, s[14:15]
	v_cndmask_b32_e64 v230, v210, v50, s[12:13]
	s_waitcnt vmcnt(8)
	v_max3_f32 v50, v211, v230, v227
	s_waitcnt lgkmcnt(0)
	v_mfma_f32_32x32x16_bf16 v[66:81], v[6:9], v[146:149], v[66:81]
	ds_read_b128 v[6:9], v10 offset:2048
	s_waitcnt lgkmcnt(0)
	v_mfma_f32_32x32x16_bf16 v[66:81], v[6:9], v[150:153], v[66:81]
	ds_read_b128 v[6:9], v10 offset:3072
	v_add_u32_e32 v10, s52, v202
	s_waitcnt lgkmcnt(0)
	v_mfma_f32_32x32x16_bf16 v[66:81], v[6:9], v[154:157], v[66:81]
	ds_read_b128 v[6:9], v10
	s_waitcnt lgkmcnt(0)
	v_mfma_f32_32x32x16_bf16 v[34:49], v[6:9], v[2:5], 0
	ds_read_b128 v[6:9], v10 offset:1024
	s_waitcnt lgkmcnt(0)
	v_mfma_f32_32x32x16_bf16 v[34:49], v[6:9], v[146:149], v[34:49]
	ds_read_b128 v[6:9], v10 offset:2048
	s_waitcnt lgkmcnt(0)
	v_mfma_f32_32x32x16_bf16 v[34:49], v[6:9], v[150:153], v[34:49]
	ds_read_b128 v[6:9], v10 offset:3072
	v_add_u32_e32 v10, s53, v202
	s_waitcnt lgkmcnt(0)
	v_mfma_f32_32x32x16_bf16 v[34:49], v[6:9], v[154:157], v[34:49]
	ds_read_b128 v[6:9], v10
	s_waitcnt lgkmcnt(0)
	v_mfma_f32_32x32x16_bf16 v[18:33], v[6:9], v[2:5], 0
	ds_read_b128 v[6:9], v10 offset:1024
	s_waitcnt lgkmcnt(0)
	v_mfma_f32_32x32x16_bf16 v[18:33], v[6:9], v[146:149], v[18:33]
	ds_read_b128 v[6:9], v10 offset:2048
	s_waitcnt lgkmcnt(0)
	v_mfma_f32_32x32x16_bf16 v[18:33], v[6:9], v[150:153], v[18:33]
	ds_read_b128 v[6:9], v10 offset:3072
	s_waitcnt lgkmcnt(0)
	v_mfma_f32_32x32x16_bf16 v[18:33], v[6:9], v[154:157], v[18:33]
	ds_read_b128 v[6:9], v175
	s_waitcnt lgkmcnt(0)
	v_mfma_f32_32x32x16_bf16 v[2:17], v[6:9], v[2:5], 0
	v_mfma_f32_32x32x16_bf16 v[2:17], v[216:219], v[146:149], v[2:17]
	ds_read_b128 v[146:149], v175 offset:2048
	s_waitcnt lgkmcnt(0)
	v_mfma_f32_32x32x16_bf16 v[2:17], v[146:149], v[150:153], v[2:17]
	ds_read_b128 v[146:149], v175 offset:3072
	s_waitcnt lgkmcnt(0)
	v_mfma_f32_32x32x16_bf16 v[2:17], v[146:149], v[154:157], v[2:17]
	v_or_b32_e32 v146, s18, v162
	v_or_b32_e32 v51, 2, v146
	v_cmp_gt_u32_e32 vcc, v51, v215
	s_and_b64 vcc, s[26:27], vcc
	v_or_b32_e32 v51, 3, v146
	v_cndmask_b32_e32 v228, v210, v52, vcc
	v_cmp_gt_u32_e32 vcc, v51, v215
	s_and_b64 vcc, s[26:27], vcc
	v_or_b32_e32 v51, 8, v146
	v_cndmask_b32_e32 v229, v210, v53, vcc
	v_cmp_gt_u32_e32 vcc, v51, v215
	s_and_b64 vcc, s[26:27], vcc
	v_or_b32_e32 v51, 9, v146
	v_cndmask_b32_e32 v224, v210, v54, vcc
	v_cmp_gt_u32_e32 vcc, v51, v215
	s_and_b64 vcc, s[26:27], vcc
	v_or_b32_e32 v51, 10, v146
	v_cndmask_b32_e32 v225, v210, v55, vcc
	v_cmp_gt_u32_e32 vcc, v51, v215
	s_and_b64 vcc, s[26:27], vcc
	v_or_b32_e32 v51, 11, v146
	v_cndmask_b32_e32 v226, v210, v56, vcc
	v_cmp_gt_u32_e32 vcc, v51, v215
	s_and_b64 vcc, s[26:27], vcc
	v_or_b32_e32 v51, 16, v146
	v_cndmask_b32_e32 v223, v210, v57, vcc
	v_cmp_gt_u32_e32 vcc, v51, v215
	s_and_b64 vcc, s[26:27], vcc
	v_or_b32_e32 v51, 17, v146
	v_cndmask_b32_e32 v222, v210, v58, vcc
	v_cmp_gt_u32_e32 vcc, v51, v215
	s_and_b64 vcc, s[26:27], vcc
	v_or_b32_e32 v51, 18, v146
	v_cndmask_b32_e32 v221, v210, v59, vcc
	v_cmp_gt_u32_e32 vcc, v51, v215
	s_and_b64 vcc, s[26:27], vcc
	v_or_b32_e32 v51, 19, v146
	v_cndmask_b32_e32 v220, v210, v60, vcc
	v_cmp_gt_u32_e32 vcc, v51, v215
	s_and_b64 vcc, s[26:27], vcc
	v_or_b32_e32 v51, 24, v146
	v_cndmask_b32_e32 v219, v210, v61, vcc
	v_cmp_gt_u32_e32 vcc, v51, v215
	s_and_b64 vcc, s[26:27], vcc
	v_or_b32_e32 v51, 25, v146
	v_cndmask_b32_e32 v218, v210, v62, vcc
	v_cmp_gt_u32_e32 vcc, v51, v215
	s_and_b64 vcc, s[26:27], vcc
	v_or_b32_e32 v51, 26, v146
	v_cndmask_b32_e32 v217, v210, v63, vcc
	v_cmp_gt_u32_e32 vcc, v51, v215
	s_and_b64 vcc, s[26:27], vcc
	v_or_b32_e32 v51, 27, v146
	v_cndmask_b32_e32 v216, v210, v64, vcc
	v_cmp_gt_u32_e32 vcc, v51, v215
	s_and_b64 vcc, s[26:27], vcc
	v_lshl_or_b32 v51, s0, 5, v162
	v_cndmask_b32_e32 v175, v210, v65, vcc
	v_cmp_gt_u32_e32 vcc, v51, v215
	v_cmp_le_u32_e64 s[18:19], v51, v231
	s_and_b64 s[18:19], vcc, s[18:19]
	s_cmp_gt_u32 s57, 2
	s_cselect_b64 s[62:63], -1, 0
	s_or_b64 s[62:63], s[26:27], s[62:63]
	s_and_b64 vcc, s[62:63], s[18:19]
	v_cndmask_b32_e32 v157, v210, v66, vcc
	v_cmp_ge_u32_e32 vcc, v51, v215
	v_cmp_lt_u32_e64 s[18:19], v51, v231
	s_and_b64 s[18:19], vcc, s[18:19]
	v_cmp_lt_u32_e32 vcc, s38, v51
	s_or_b64 s[64:65], s[26:27], vcc
	s_and_b64 vcc, s[18:19], s[64:65]
	v_or_b32_e32 v52, 2, v51
	v_cndmask_b32_e32 v156, v210, v67, vcc
	v_cmp_gt_u32_e32 vcc, v52, v215
	v_cmp_le_u32_e64 s[18:19], v52, v231
	s_and_b64 s[18:19], vcc, s[18:19]
	s_and_b64 vcc, s[62:63], s[18:19]
	v_or_b32_e32 v52, 3, v51
	v_cndmask_b32_e32 v155, v210, v68, vcc
	v_cmp_gt_u32_e32 vcc, v52, v215
	v_cmp_le_u32_e64 s[18:19], v52, v231
	s_and_b64 s[18:19], vcc, s[18:19]
	s_and_b64 vcc, s[62:63], s[18:19]
	v_or_b32_e32 v52, 8, v51
	v_cndmask_b32_e32 v154, v210, v69, vcc
	v_cmp_gt_u32_e32 vcc, v52, v215
	v_cmp_le_u32_e64 s[18:19], v52, v231
	s_and_b64 s[18:19], vcc, s[18:19]
	s_and_b64 vcc, s[62:63], s[18:19]
	v_or_b32_e32 v52, 9, v51
	v_cndmask_b32_e32 v150, v210, v70, vcc
	v_cmp_gt_u32_e32 vcc, v52, v215
	v_cmp_le_u32_e64 s[18:19], v52, v231
	s_and_b64 s[18:19], vcc, s[18:19]
	v_cmp_lt_u32_e32 vcc, s39, v51
	s_or_b64 s[64:65], s[26:27], vcc
	s_and_b64 vcc, s[64:65], s[18:19]
	v_or_b32_e32 v52, 10, v51
	v_cndmask_b32_e32 v151, v210, v71, vcc
	v_cmp_gt_u32_e32 vcc, v52, v215
	v_cmp_le_u32_e64 s[18:19], v52, v231
	s_and_b64 s[18:19], vcc, s[18:19]
	v_cmp_lt_u32_e32 vcc, s40, v51
	s_or_b64 s[64:65], s[26:27], vcc
	s_and_b64 vcc, s[64:65], s[18:19]
	v_or_b32_e32 v52, 11, v51
	v_cndmask_b32_e32 v152, v210, v72, vcc
	v_cmp_gt_u32_e32 vcc, v52, v215
	v_cmp_le_u32_e64 s[18:19], v52, v231
	s_and_b64 s[18:19], vcc, s[18:19]
	v_cmp_lt_u32_e32 vcc, s41, v51
	s_or_b64 s[64:65], s[26:27], vcc
	s_and_b64 vcc, s[64:65], s[18:19]
	v_or_b32_e32 v52, 16, v51
	v_cndmask_b32_e32 v153, v210, v73, vcc
	v_cmp_gt_u32_e32 vcc, v52, v215
	v_cmp_le_u32_e64 s[18:19], v52, v231
	s_and_b64 s[18:19], vcc, s[18:19]
	s_and_b64 vcc, s[62:63], s[18:19]
	v_or_b32_e32 v52, 17, v51
	v_cndmask_b32_e32 v146, v210, v74, vcc
	v_cmp_gt_u32_e32 vcc, v52, v215
	v_cmp_le_u32_e64 s[18:19], v52, v231
	s_and_b64 s[18:19], vcc, s[18:19]
	v_cmp_lt_u32_e32 vcc, s42, v51
	s_or_b64 s[64:65], s[26:27], vcc
	s_and_b64 vcc, s[64:65], s[18:19]
	v_or_b32_e32 v52, 18, v51
	v_cndmask_b32_e32 v147, v210, v75, vcc
	v_cmp_gt_u32_e32 vcc, v52, v215
	v_cmp_le_u32_e64 s[18:19], v52, v231
	s_and_b64 s[18:19], vcc, s[18:19]
	v_cmp_lt_u32_e32 vcc, s43, v51
	s_or_b64 s[64:65], s[26:27], vcc
	s_and_b64 vcc, s[64:65], s[18:19]
	v_or_b32_e32 v52, 19, v51
	v_cndmask_b32_e32 v148, v210, v76, vcc
	v_cmp_gt_u32_e32 vcc, v52, v215
	v_cmp_le_u32_e64 s[18:19], v52, v231
	s_and_b64 s[18:19], vcc, s[18:19]
	v_cmp_lt_u32_e32 vcc, s44, v51
	s_or_b64 s[64:65], s[26:27], vcc
	s_and_b64 vcc, s[64:65], s[18:19]
	v_or_b32_e32 v52, 24, v51
	v_cndmask_b32_e32 v149, v210, v77, vcc
	v_cmp_gt_u32_e32 vcc, v52, v215
	v_cmp_le_u32_e64 s[18:19], v52, v231
	s_and_b64 s[18:19], vcc, s[18:19]
	s_and_b64 vcc, s[62:63], s[18:19]
	v_or_b32_e32 v52, 25, v51
	v_cndmask_b32_e32 v72, v210, v78, vcc
	v_cmp_gt_u32_e32 vcc, v52, v215
	v_cmp_le_u32_e64 s[18:19], v52, v231
	s_and_b64 s[18:19], vcc, s[18:19]
	v_cmp_lt_u32_e32 vcc, s45, v51
	s_or_b64 s[62:63], s[26:27], vcc
	s_and_b64 vcc, s[62:63], s[18:19]
	v_or_b32_e32 v52, 26, v51
	v_cndmask_b32_e32 v73, v210, v79, vcc
	v_cmp_gt_u32_e32 vcc, v52, v215
	v_cmp_le_u32_e64 s[18:19], v52, v231
	s_and_b64 s[18:19], vcc, s[18:19]
	v_cmp_lt_u32_e32 vcc, s46, v51
	s_or_b64 s[62:63], s[26:27], vcc
	s_and_b64 vcc, s[62:63], s[18:19]
	v_or_b32_e32 v52, 27, v51
	v_cndmask_b32_e32 v76, v210, v80, vcc
	v_cmp_gt_u32_e32 vcc, v52, v215
	v_cmp_le_u32_e64 s[18:19], v52, v231
	s_and_b64 s[18:19], vcc, s[18:19]
	v_cmp_lt_u32_e32 vcc, s47, v51
	s_or_b64 s[62:63], s[26:27], vcc
	s_and_b64 vcc, s[62:63], s[18:19]
	v_lshl_or_b32 v51, s60, 5, v162
	v_cndmask_b32_e32 v77, v210, v81, vcc
	v_cmp_gt_u32_e32 vcc, v51, v215
	v_cmp_le_u32_e64 s[18:19], v51, v231
	s_and_b64 s[18:19], vcc, s[18:19]
	s_cmp_gt_u32 s57, 1
	s_cselect_b64 s[60:61], -1, 0
	s_or_b64 s[60:61], s[26:27], s[60:61]
	s_and_b64 vcc, s[60:61], s[18:19]
	v_cndmask_b32_e32 v78, v210, v34, vcc
	v_cmp_ge_u32_e32 vcc, v51, v215
	v_cmp_lt_u32_e64 s[18:19], v51, v231
	s_and_b64 s[18:19], vcc, s[18:19]
	v_cmp_lt_u32_e32 vcc, s38, v51
	s_or_b64 s[62:63], s[26:27], vcc
	s_and_b64 vcc, s[18:19], s[62:63]
	v_cndmask_b32_e32 v74, v210, v35, vcc
	v_or_b32_e32 v35, 2, v51
	v_cmp_gt_u32_e32 vcc, v35, v215
	v_cmp_le_u32_e64 s[18:19], v35, v231
	s_and_b64 s[18:19], vcc, s[18:19]
	s_and_b64 vcc, s[60:61], s[18:19]
	v_or_b32_e32 v35, 3, v51
	v_cndmask_b32_e32 v71, v210, v36, vcc
	v_cmp_gt_u32_e32 vcc, v35, v215
	v_cmp_le_u32_e64 s[18:19], v35, v231
	s_and_b64 s[18:19], vcc, s[18:19]
	s_and_b64 vcc, s[60:61], s[18:19]
	v_or_b32_e32 v35, 8, v51
	v_cndmask_b32_e32 v69, v210, v37, vcc
	v_cmp_gt_u32_e32 vcc, v35, v215
	v_cmp_le_u32_e64 s[18:19], v35, v231
	s_and_b64 s[18:19], vcc, s[18:19]
	s_and_b64 vcc, s[60:61], s[18:19]
	v_or_b32_e32 v35, 9, v51
	v_cndmask_b32_e32 v55, v210, v38, vcc
	v_cmp_gt_u32_e32 vcc, v35, v215
	v_cmp_le_u32_e64 s[18:19], v35, v231
	s_and_b64 s[18:19], vcc, s[18:19]
	v_cmp_lt_u32_e32 vcc, s39, v51
	s_or_b64 s[62:63], s[26:27], vcc
	s_and_b64 vcc, s[62:63], s[18:19]
	v_or_b32_e32 v35, 10, v51
	v_cndmask_b32_e32 v56, v210, v39, vcc
	v_cmp_gt_u32_e32 vcc, v35, v215
	v_cmp_le_u32_e64 s[18:19], v35, v231
	s_and_b64 s[18:19], vcc, s[18:19]
	v_cmp_lt_u32_e32 vcc, s40, v51
	s_or_b64 s[62:63], s[26:27], vcc
	s_and_b64 vcc, s[62:63], s[18:19]
	v_or_b32_e32 v35, 11, v51
	v_cndmask_b32_e32 v61, v210, v40, vcc
	v_cmp_gt_u32_e32 vcc, v35, v215
	v_cmp_le_u32_e64 s[18:19], v35, v231
	s_and_b64 s[18:19], vcc, s[18:19]
	v_cmp_lt_u32_e32 vcc, s41, v51
	s_or_b64 s[62:63], s[26:27], vcc
	s_and_b64 vcc, s[62:63], s[18:19]
	v_or_b32_e32 v35, 16, v51
	v_cndmask_b32_e32 v62, v210, v41, vcc
	v_cmp_gt_u32_e32 vcc, v35, v215
	v_cmp_le_u32_e64 s[18:19], v35, v231
	s_and_b64 s[18:19], vcc, s[18:19]
	s_and_b64 vcc, s[60:61], s[18:19]
	v_or_b32_e32 v35, 17, v51
	v_cndmask_b32_e32 v57, v210, v42, vcc
	v_cmp_gt_u32_e32 vcc, v35, v215
	v_cmp_le_u32_e64 s[18:19], v35, v231
	s_and_b64 s[18:19], vcc, s[18:19]
	v_cmp_lt_u32_e32 vcc, s42, v51
	s_or_b64 s[62:63], s[26:27], vcc
	s_and_b64 vcc, s[62:63], s[18:19]
	v_or_b32_e32 v35, 18, v51
	v_cndmask_b32_e32 v58, v210, v43, vcc
	v_cmp_gt_u32_e32 vcc, v35, v215
	v_cmp_le_u32_e64 s[18:19], v35, v231
	s_and_b64 s[18:19], vcc, s[18:19]
	v_cmp_lt_u32_e32 vcc, s43, v51
	s_or_b64 s[62:63], s[26:27], vcc
	s_and_b64 vcc, s[62:63], s[18:19]
	v_or_b32_e32 v35, 19, v51
	v_cndmask_b32_e32 v63, v210, v44, vcc
	v_cmp_gt_u32_e32 vcc, v35, v215
	v_cmp_le_u32_e64 s[18:19], v35, v231
	s_and_b64 s[18:19], vcc, s[18:19]
	v_cmp_lt_u32_e32 vcc, s44, v51
	s_or_b64 s[62:63], s[26:27], vcc
	s_and_b64 vcc, s[62:63], s[18:19]
	v_or_b32_e32 v35, 24, v51
	v_cndmask_b32_e32 v64, v210, v45, vcc
	v_cmp_gt_u32_e32 vcc, v35, v215
	v_cmp_le_u32_e64 s[18:19], v35, v231
	s_and_b64 s[18:19], vcc, s[18:19]
	s_and_b64 vcc, s[60:61], s[18:19]
	v_or_b32_e32 v35, 25, v51
	v_cndmask_b32_e32 v59, v210, v46, vcc
	v_cmp_gt_u32_e32 vcc, v35, v215
	v_cmp_le_u32_e64 s[18:19], v35, v231
	s_and_b64 s[18:19], vcc, s[18:19]
	v_cmp_lt_u32_e32 vcc, s45, v51
	s_or_b64 s[60:61], s[26:27], vcc
	s_and_b64 vcc, s[60:61], s[18:19]
	v_or_b32_e32 v35, 26, v51
	v_cndmask_b32_e32 v60, v210, v47, vcc
	v_cmp_gt_u32_e32 vcc, v35, v215
	v_cmp_le_u32_e64 s[18:19], v35, v231
	s_and_b64 s[18:19], vcc, s[18:19]
	v_cmp_lt_u32_e32 vcc, s46, v51
	s_or_b64 s[60:61], s[26:27], vcc
	s_and_b64 vcc, s[60:61], s[18:19]
	v_or_b32_e32 v35, 27, v51
	v_cndmask_b32_e32 v65, v210, v48, vcc
	v_cmp_gt_u32_e32 vcc, v35, v215
	v_cmp_le_u32_e64 s[18:19], v35, v231
	s_and_b64 s[18:19], vcc, s[18:19]
	v_cmp_lt_u32_e32 vcc, s47, v51
	s_or_b64 s[60:61], s[26:27], vcc
	s_and_b64 vcc, s[60:61], s[18:19]
	v_lshl_or_b32 v35, s59, 5, v162
	v_cndmask_b32_e32 v66, v210, v49, vcc
	v_cmp_gt_u32_e32 vcc, v35, v215
	v_cmp_le_u32_e64 s[18:19], v35, v231
	s_and_b64 s[18:19], vcc, s[18:19]
	s_or_b32 s57, s57, s50
	s_cmp_lg_u32 s57, 0
	s_cselect_b64 s[60:61], -1, 0
	s_and_b64 vcc, s[60:61], s[18:19]
	v_cndmask_b32_e32 v70, v210, v18, vcc
	v_cmp_ge_u32_e32 vcc, v35, v215
	v_cmp_lt_u32_e64 s[18:19], v35, v231
	s_and_b64 s[18:19], vcc, s[18:19]
	v_cmp_lt_u32_e32 vcc, s38, v35
	s_or_b64 s[62:63], s[26:27], vcc
	s_and_b64 vcc, s[18:19], s[62:63]
	v_cndmask_b32_e32 v68, v210, v19, vcc
	v_or_b32_e32 v19, 2, v35
	v_cmp_gt_u32_e32 vcc, v19, v215
	v_cmp_le_u32_e64 s[18:19], v19, v231
	s_and_b64 s[18:19], vcc, s[18:19]
	s_and_b64 vcc, s[60:61], s[18:19]
	v_or_b32_e32 v19, 3, v35
	v_cndmask_b32_e32 v67, v210, v20, vcc
	v_cmp_gt_u32_e32 vcc, v19, v215
	v_cmp_le_u32_e64 s[18:19], v19, v231
	s_and_b64 s[18:19], vcc, s[18:19]
	s_and_b64 vcc, s[60:61], s[18:19]
	v_or_b32_e32 v19, 8, v35
	v_max3_f32 v50, v50, v228, v229
	v_cndmask_b32_e32 v48, v210, v21, vcc
	v_cmp_gt_u32_e32 vcc, v19, v215
	v_cmp_le_u32_e64 s[18:19], v19, v231
	v_max3_f32 v50, v50, v224, v225
	s_and_b64 s[18:19], vcc, s[18:19]
	v_max3_f32 v50, v50, v226, v223
	s_and_b64 vcc, s[60:61], s[18:19]
	v_or_b32_e32 v19, 9, v35
	v_max3_f32 v50, v50, v222, v221
	v_cndmask_b32_e32 v42, v210, v22, vcc
	v_cmp_gt_u32_e32 vcc, v19, v215
	v_cmp_le_u32_e64 s[18:19], v19, v231
	v_max3_f32 v50, v50, v220, v219
	s_and_b64 s[18:19], vcc, s[18:19]
	v_cmp_lt_u32_e32 vcc, s39, v35
	v_max3_f32 v50, v50, v218, v217
	s_or_b64 s[62:63], s[26:27], vcc
	v_max3_f32 v50, v50, v216, v175
	s_and_b64 vcc, s[62:63], s[18:19]
	v_or_b32_e32 v19, 10, v35
	v_max3_f32 v50, v50, v157, v156
	v_cndmask_b32_e32 v43, v210, v23, vcc
	v_cmp_gt_u32_e32 vcc, v19, v215
	v_cmp_le_u32_e64 s[18:19], v19, v231
	v_max3_f32 v50, v50, v155, v154
	s_and_b64 s[18:19], vcc, s[18:19]
	v_cmp_lt_u32_e32 vcc, s40, v35
	v_max3_f32 v50, v50, v150, v151
	s_or_b64 s[62:63], s[26:27], vcc
	v_max3_f32 v50, v50, v152, v153
	s_and_b64 vcc, s[62:63], s[18:19]
	v_or_b32_e32 v19, 11, v35
	v_max3_f32 v50, v50, v146, v147
	v_cndmask_b32_e32 v49, v210, v24, vcc
	v_cmp_gt_u32_e32 vcc, v19, v215
	v_cmp_le_u32_e64 s[18:19], v19, v231
	v_max3_f32 v50, v50, v148, v149
	s_and_b64 s[18:19], vcc, s[18:19]
	v_cmp_lt_u32_e32 vcc, s41, v35
	v_max3_f32 v50, v50, v72, v73
	s_or_b64 s[62:63], s[26:27], vcc
	v_max3_f32 v50, v50, v76, v77
	s_and_b64 vcc, s[62:63], s[18:19]
	v_or_b32_e32 v19, 16, v35
	v_max3_f32 v34, v50, v78, v74
	v_cndmask_b32_e32 v50, v210, v25, vcc
	v_cmp_gt_u32_e32 vcc, v19, v215
	v_cmp_le_u32_e64 s[18:19], v19, v231
	s_and_b64 s[18:19], vcc, s[18:19]
	s_and_b64 vcc, s[60:61], s[18:19]
	v_or_b32_e32 v19, 17, v35
	v_cndmask_b32_e32 v44, v210, v26, vcc
	v_cmp_gt_u32_e32 vcc, v19, v215
	v_cmp_le_u32_e64 s[18:19], v19, v231
	s_and_b64 s[18:19], vcc, s[18:19]
	v_cmp_lt_u32_e32 vcc, s42, v35
	s_or_b64 s[62:63], s[26:27], vcc
	s_and_b64 vcc, s[62:63], s[18:19]
	v_or_b32_e32 v19, 18, v35
	v_cndmask_b32_e32 v45, v210, v27, vcc
	v_cmp_gt_u32_e32 vcc, v19, v215
	v_cmp_le_u32_e64 s[18:19], v19, v231
	s_and_b64 s[18:19], vcc, s[18:19]
	v_cmp_lt_u32_e32 vcc, s43, v35
	s_or_b64 s[62:63], s[26:27], vcc
	s_and_b64 vcc, s[62:63], s[18:19]
	v_or_b32_e32 v19, 19, v35
	v_cndmask_b32_e32 v51, v210, v28, vcc
	v_cmp_gt_u32_e32 vcc, v19, v215
	v_cmp_le_u32_e64 s[18:19], v19, v231
	s_and_b64 s[18:19], vcc, s[18:19]
	v_cmp_lt_u32_e32 vcc, s44, v35
	s_or_b64 s[62:63], s[26:27], vcc
	s_and_b64 vcc, s[62:63], s[18:19]
	v_or_b32_e32 v19, 24, v35
	v_cndmask_b32_e32 v52, v210, v29, vcc
	v_cmp_gt_u32_e32 vcc, v19, v215
	v_cmp_le_u32_e64 s[18:19], v19, v231
	s_and_b64 s[18:19], vcc, s[18:19]
	s_and_b64 vcc, s[60:61], s[18:19]
	v_or_b32_e32 v19, 25, v35
	v_cndmask_b32_e32 v46, v210, v30, vcc
	v_cmp_gt_u32_e32 vcc, v19, v215
	v_cmp_le_u32_e64 s[18:19], v19, v231
	s_and_b64 s[18:19], vcc, s[18:19]
	v_cmp_lt_u32_e32 vcc, s45, v35
	s_or_b64 s[60:61], s[26:27], vcc
	s_and_b64 vcc, s[60:61], s[18:19]
	v_or_b32_e32 v19, 26, v35
	v_cndmask_b32_e32 v47, v210, v31, vcc
	v_cmp_gt_u32_e32 vcc, v19, v215
	v_cmp_le_u32_e64 s[18:19], v19, v231
	s_and_b64 s[18:19], vcc, s[18:19]
	v_cmp_lt_u32_e32 vcc, s46, v35
	s_or_b64 s[60:61], s[26:27], vcc
	s_and_b64 vcc, s[60:61], s[18:19]
	v_or_b32_e32 v19, 27, v35
	v_max3_f32 v34, v34, v71, v69
	v_cndmask_b32_e32 v53, v210, v32, vcc
	v_cmp_gt_u32_e32 vcc, v19, v215
	v_cmp_le_u32_e64 s[18:19], v19, v231
	v_max3_f32 v34, v34, v55, v56
	s_and_b64 s[18:19], vcc, s[18:19]
	v_cmp_lt_u32_e32 vcc, s47, v35
	v_max3_f32 v34, v34, v61, v62
	s_or_b64 s[60:61], s[26:27], vcc
	v_max3_f32 v34, v34, v57, v58
	s_and_b64 vcc, s[60:61], s[18:19]
	v_lshl_or_b32 v22, s58, 5, v162
	v_max3_f32 v34, v34, v63, v64
	v_cndmask_b32_e32 v54, v210, v33, vcc
	v_cmp_le_u32_e32 vcc, v22, v231
	v_max3_f32 v34, v34, v59, v60
	v_max3_f32 v34, v34, v65, v66
	v_cndmask_b32_e32 v41, v210, v2, vcc
	v_cmp_lt_u32_e32 vcc, v22, v231
	v_max3_f32 v18, v34, v70, v68
	v_max3_f32 v18, v18, v67, v48
	v_cndmask_b32_e32 v39, v210, v3, vcc
	v_or_b32_e32 v3, 2, v22
	v_cmp_le_u32_e32 vcc, v3, v231
	v_or_b32_e32 v3, 3, v22
	v_max3_f32 v18, v18, v42, v43
	v_cndmask_b32_e32 v38, v210, v4, vcc
	v_cmp_le_u32_e32 vcc, v3, v231
	v_or_b32_e32 v3, 8, v22
	v_max3_f32 v18, v18, v49, v50
	v_cndmask_b32_e32 v36, v210, v5, vcc
	v_cmp_le_u32_e32 vcc, v3, v231
	v_or_b32_e32 v3, 9, v22
	v_max3_f32 v18, v18, v44, v45
	v_cndmask_b32_e32 v34, v210, v6, vcc
	v_cmp_le_u32_e32 vcc, v3, v231
	v_or_b32_e32 v3, 10, v22
	v_max3_f32 v18, v18, v51, v52
	v_cndmask_b32_e32 v33, v210, v7, vcc
	v_cmp_le_u32_e32 vcc, v3, v231
	v_or_b32_e32 v3, 11, v22
	v_max3_f32 v18, v18, v46, v47
	v_cndmask_b32_e32 v31, v210, v8, vcc
	v_cmp_le_u32_e32 vcc, v3, v231
	v_or_b32_e32 v3, 16, v22
	v_max3_f32 v18, v18, v53, v54
	v_cndmask_b32_e32 v30, v210, v9, vcc
	v_cmp_le_u32_e32 vcc, v3, v231
	v_or_b32_e32 v3, 17, v22
	v_max3_f32 v2, v18, v41, v39
	v_cndmask_b32_e32 v21, v210, v10, vcc
	v_cmp_le_u32_e32 vcc, v3, v231
	v_or_b32_e32 v3, 18, v22
	v_max3_f32 v2, v2, v38, v36
	v_cndmask_b32_e32 v20, v210, v11, vcc
	v_cmp_le_u32_e32 vcc, v3, v231
	v_or_b32_e32 v3, 19, v22
	v_max3_f32 v2, v2, v34, v33
	v_cndmask_b32_e32 v19, v210, v12, vcc
	v_cmp_le_u32_e32 vcc, v3, v231
	v_or_b32_e32 v3, 24, v22
	v_max3_f32 v2, v2, v31, v30
	v_cndmask_b32_e32 v18, v210, v13, vcc
	v_cmp_le_u32_e32 vcc, v3, v231
	v_or_b32_e32 v3, 25, v22
	v_max3_f32 v2, v2, v21, v20
	v_cndmask_b32_e32 v14, v210, v14, vcc
	v_cmp_le_u32_e32 vcc, v3, v231
	v_or_b32_e32 v3, 26, v22
	v_max3_f32 v2, v2, v19, v18
	v_cndmask_b32_e32 v12, v210, v15, vcc
	v_cmp_le_u32_e32 vcc, v3, v231
	v_or_b32_e32 v3, 27, v22
	v_max3_f32 v2, v2, v14, v12
	v_cndmask_b32_e32 v13, v210, v16, vcc
	v_cmp_le_u32_e32 vcc, v3, v231
	s_add_i32 s18, s29, 0
	v_add3_u32 v246, s18, v199, v200
	v_cndmask_b32_e32 v11, v210, v17, vcc
	v_max3_f32 v2, v2, v13, v11
	v_mov_b32_e32 v3, v2
	v_add3_u32 v247, s18, v201, v200
	s_add_i32 s18, s51, 0
	v_readlane_b32 s64, v249, 43
	s_mov_b32 s57, s0
	s_waitcnt lgkmcnt(0)
	v_permlane32_swap_b32_e32 v3, v2
	v_max_f32_e32 v3, v3, v3
	v_max_f32_e32 v10, v2, v3
	v_sub_f32_e32 v16, v222, v10
	v_mul_f32_e32 v16, 0x3fb8aa3b, v16
	v_exp_f32_e32 v22, v16
	v_sub_f32_e32 v16, v221, v10
	v_mul_f32_e32 v16, 0x3fb8aa3b, v16
	v_exp_f32_e32 v23, v16
	v_sub_f32_e32 v16, v220, v10
	v_mul_f32_e32 v16, 0x3fb8aa3b, v16
	v_exp_f32_e32 v24, v16
	v_sub_f32_e32 v16, v219, v10
	v_mul_f32_e32 v16, 0x3fb8aa3b, v16
	v_exp_f32_e32 v25, v16
	v_sub_f32_e32 v16, v218, v10
	v_mul_f32_e32 v16, 0x3fb8aa3b, v16
	v_exp_f32_e32 v26, v16
	v_sub_f32_e32 v16, v217, v10
	v_mul_f32_e32 v16, 0x3fb8aa3b, v16
	v_exp_f32_e32 v27, v16
	v_sub_f32_e32 v16, v216, v10
	v_mul_f32_e32 v16, 0x3fb8aa3b, v16
	v_exp_f32_e32 v28, v16
	v_sub_f32_e32 v16, v175, v10
	v_mul_f32_e32 v16, 0x3fb8aa3b, v16
	v_exp_f32_e32 v29, v16
	v_sub_f32_e32 v16, v157, v10
	v_mul_f32_e32 v16, 0x3fb8aa3b, v16
	v_exp_f32_e32 v32, v16
	v_sub_f32_e32 v16, v156, v10
	v_mul_f32_e32 v16, 0x3fb8aa3b, v16
	v_exp_f32_e32 v35, v16
	v_sub_f32_e32 v16, v155, v10
	v_mul_f32_e32 v16, 0x3fb8aa3b, v16
	v_exp_f32_e32 v37, v16
	v_sub_f32_e32 v16, v154, v10
	v_mul_f32_e32 v16, 0x3fb8aa3b, v16
	v_exp_f32_e32 v40, v16
	v_sub_f32_e32 v16, v150, v10
	v_mul_f32_e32 v16, 0x3fb8aa3b, v16
	v_exp_f32_e32 v75, v16
	v_sub_f32_e32 v16, v151, v10
	v_mul_f32_e32 v16, 0x3fb8aa3b, v16
	v_exp_f32_e32 v79, v16
	v_sub_f32_e32 v16, v152, v10
	v_sub_f32_e32 v2, v230, v10
	v_mul_f32_e32 v16, 0x3fb8aa3b, v16
	v_mul_f32_e32 v2, 0x3fb8aa3b, v2
	v_sub_f32_e32 v3, v227, v10
	v_exp_f32_e32 v80, v16
	v_sub_f32_e32 v16, v153, v10
	v_exp_f32_e32 v2, v2
	v_mul_f32_e32 v3, 0x3fb8aa3b, v3
	v_mul_f32_e32 v16, 0x3fb8aa3b, v16
	v_exp_f32_e32 v3, v3
	v_exp_f32_e32 v81, v16
	v_sub_f32_e32 v16, v146, v10
	v_mul_f32_e32 v16, 0x3fb8aa3b, v16
	v_exp_f32_e32 v146, v16
	v_sub_f32_e32 v16, v147, v10
	v_add_f32_e32 v4, 0, v2
	v_mul_f32_e32 v16, 0x3fb8aa3b, v16
	v_add_f32_e32 v5, v3, v4
	v_sub_f32_e32 v4, v228, v10
	v_exp_f32_e32 v147, v16
	v_sub_f32_e32 v16, v148, v10
	v_mul_f32_e32 v4, 0x3fb8aa3b, v4
	v_mul_f32_e32 v16, 0x3fb8aa3b, v16
	v_exp_f32_e32 v4, v4
	v_exp_f32_e32 v148, v16
	v_sub_f32_e32 v16, v149, v10
	v_mul_f32_e32 v16, 0x3fb8aa3b, v16
	v_exp_f32_e32 v149, v16
	v_sub_f32_e32 v16, v72, v10
	v_mul_f32_e32 v16, 0x3fb8aa3b, v16
	v_add_f32_e32 v6, v4, v5
	v_sub_f32_e32 v5, v229, v10
	v_exp_f32_e32 v150, v16
	v_sub_f32_e32 v16, v73, v10
	v_mul_f32_e32 v5, 0x3fb8aa3b, v5
	v_mul_f32_e32 v16, 0x3fb8aa3b, v16
	v_exp_f32_e32 v5, v5
	v_exp_f32_e32 v73, v16
	v_sub_f32_e32 v16, v76, v10
	v_mul_f32_e32 v16, 0x3fb8aa3b, v16
	v_exp_f32_e32 v76, v16
	v_sub_f32_e32 v16, v77, v10
	v_mul_f32_e32 v16, 0x3fb8aa3b, v16
	v_add_f32_e32 v7, v5, v6
	v_sub_f32_e32 v6, v224, v10
	v_exp_f32_e32 v77, v16
	v_sub_f32_e32 v16, v78, v10
	v_mul_f32_e32 v6, 0x3fb8aa3b, v6
	v_mul_f32_e32 v16, 0x3fb8aa3b, v16
	v_exp_f32_e32 v6, v6
	v_exp_f32_e32 v152, v16
	v_sub_f32_e32 v16, v74, v10
	v_mul_f32_e32 v16, 0x3fb8aa3b, v16
	v_exp_f32_e32 v74, v16
	v_sub_f32_e32 v16, v71, v10
	v_mul_f32_e32 v16, 0x3fb8aa3b, v16
	v_add_f32_e32 v8, v6, v7
	v_sub_f32_e32 v7, v225, v10
	v_exp_f32_e32 v154, v16
	v_sub_f32_e32 v16, v69, v10
	v_mul_f32_e32 v7, 0x3fb8aa3b, v7
	v_mul_f32_e32 v16, 0x3fb8aa3b, v16
	v_exp_f32_e32 v7, v7
	v_exp_f32_e32 v155, v16
	v_sub_f32_e32 v16, v55, v10
	v_mul_f32_e32 v16, 0x3fb8aa3b, v16
	v_exp_f32_e32 v156, v16
	v_sub_f32_e32 v16, v56, v10
	v_mul_f32_e32 v16, 0x3fb8aa3b, v16
	v_add_f32_e32 v9, v7, v8
	v_sub_f32_e32 v8, v226, v10
	v_exp_f32_e32 v56, v16
	v_sub_f32_e32 v16, v61, v10
	v_mul_f32_e32 v8, 0x3fb8aa3b, v8
	v_mul_f32_e32 v16, 0x3fb8aa3b, v16
	v_exp_f32_e32 v8, v8
	v_exp_f32_e32 v157, v16
	v_sub_f32_e32 v16, v62, v10
	v_mul_f32_e32 v16, 0x3fb8aa3b, v16
	v_exp_f32_e32 v175, v16
	v_sub_f32_e32 v16, v57, v10
	v_mul_f32_e32 v16, 0x3fb8aa3b, v16
	v_add_f32_e32 v15, v8, v9
	v_sub_f32_e32 v9, v223, v10
	v_exp_f32_e32 v215, v16
	v_sub_f32_e32 v16, v58, v10
	v_mul_f32_e32 v9, 0x3fb8aa3b, v9
	v_mul_f32_e32 v16, 0x3fb8aa3b, v16
	v_exp_f32_e32 v9, v9
	v_exp_f32_e32 v216, v16
	v_sub_f32_e32 v16, v63, v10
	v_mul_f32_e32 v16, 0x3fb8aa3b, v16
	v_exp_f32_e32 v217, v16
	v_sub_f32_e32 v16, v64, v10
	v_mul_f32_e32 v16, 0x3fb8aa3b, v16
	v_add_f32_e32 v15, v9, v15
	v_exp_f32_e32 v218, v16
	v_sub_f32_e32 v16, v59, v10
	v_add_f32_e32 v15, v22, v15
	v_mul_f32_e32 v16, 0x3fb8aa3b, v16
	v_add_f32_e32 v15, v23, v15
	v_exp_f32_e32 v219, v16
	v_sub_f32_e32 v16, v60, v10
	v_add_f32_e32 v15, v24, v15
	v_mul_f32_e32 v16, 0x3fb8aa3b, v16
	v_add_f32_e32 v15, v25, v15
	v_exp_f32_e32 v220, v16
	v_sub_f32_e32 v16, v65, v10
	v_add_f32_e32 v15, v26, v15
	v_mul_f32_e32 v16, 0x3fb8aa3b, v16
	v_add_f32_e32 v15, v27, v15
	v_exp_f32_e32 v221, v16
	v_sub_f32_e32 v16, v66, v10
	v_add_f32_e32 v15, v28, v15
	v_mul_f32_e32 v16, 0x3fb8aa3b, v16
	v_add_f32_e32 v15, v29, v15
	v_exp_f32_e32 v222, v16
	v_sub_f32_e32 v16, v70, v10
	v_add_f32_e32 v15, v32, v15
	v_mul_f32_e32 v16, 0x3fb8aa3b, v16
	v_add_f32_e32 v15, v35, v15
	v_exp_f32_e32 v223, v16
	v_sub_f32_e32 v16, v68, v10
	v_add_f32_e32 v15, v37, v15
	v_mul_f32_e32 v16, 0x3fb8aa3b, v16
	v_add_f32_e32 v15, v40, v15
	v_exp_f32_e32 v224, v16
	v_sub_f32_e32 v16, v67, v10
	v_add_f32_e32 v15, v75, v15
	v_mul_f32_e32 v16, 0x3fb8aa3b, v16
	v_add_f32_e32 v15, v79, v15
	v_exp_f32_e32 v225, v16
	v_sub_f32_e32 v16, v48, v10
	v_add_f32_e32 v15, v80, v15
	v_mul_f32_e32 v16, 0x3fb8aa3b, v16
	v_add_f32_e32 v15, v81, v15
	v_exp_f32_e32 v48, v16
	v_sub_f32_e32 v16, v42, v10
	v_add_f32_e32 v15, v146, v15
	v_mul_f32_e32 v16, 0x3fb8aa3b, v16
	v_add_f32_e32 v15, v147, v15
	v_exp_f32_e32 v226, v16
	v_sub_f32_e32 v16, v43, v10
	v_add_f32_e32 v15, v148, v15
	v_mul_f32_e32 v16, 0x3fb8aa3b, v16
	v_add_f32_e32 v15, v149, v15
	v_exp_f32_e32 v227, v16
	v_sub_f32_e32 v16, v49, v10
	v_add_f32_e32 v15, v150, v15
	v_mul_f32_e32 v16, 0x3fb8aa3b, v16
	v_add_f32_e32 v15, v73, v15
	v_exp_f32_e32 v49, v16
	v_sub_f32_e32 v16, v50, v10
	v_add_f32_e32 v15, v76, v15
	v_mul_f32_e32 v16, 0x3fb8aa3b, v16
	v_add_f32_e32 v15, v77, v15
	v_exp_f32_e32 v228, v16
	v_sub_f32_e32 v16, v44, v10
	v_add_f32_e32 v15, v152, v15
	v_mul_f32_e32 v16, 0x3fb8aa3b, v16
	v_add_f32_e32 v15, v74, v15
	v_exp_f32_e32 v229, v16
	v_sub_f32_e32 v16, v45, v10
	v_add_f32_e32 v15, v154, v15
	v_mul_f32_e32 v16, 0x3fb8aa3b, v16
	v_add_f32_e32 v15, v155, v15
	v_exp_f32_e32 v230, v16
	v_sub_f32_e32 v16, v51, v10
	v_add_f32_e32 v15, v156, v15
	v_mul_f32_e32 v16, 0x3fb8aa3b, v16
	v_add_f32_e32 v15, v56, v15
	v_exp_f32_e32 v231, v16
	v_sub_f32_e32 v16, v52, v10
	v_add_f32_e32 v15, v157, v15
	v_mul_f32_e32 v16, 0x3fb8aa3b, v16
	v_add_f32_e32 v15, v175, v15
	v_exp_f32_e32 v232, v16
	v_sub_f32_e32 v16, v46, v10
	v_add_f32_e32 v15, v215, v15
	v_mul_f32_e32 v16, 0x3fb8aa3b, v16
	v_add_f32_e32 v15, v216, v15
	v_exp_f32_e32 v233, v16
	v_sub_f32_e32 v16, v47, v10
	v_add_f32_e32 v15, v217, v15
	v_mul_f32_e32 v16, 0x3fb8aa3b, v16
	v_add_f32_e32 v15, v218, v15
	v_exp_f32_e32 v234, v16
	v_sub_f32_e32 v16, v53, v10
	v_add_f32_e32 v15, v219, v15
	v_mul_f32_e32 v16, 0x3fb8aa3b, v16
	v_add_f32_e32 v15, v220, v15
	v_exp_f32_e32 v235, v16
	v_sub_f32_e32 v16, v54, v10
	v_add_f32_e32 v15, v221, v15
	v_mul_f32_e32 v16, 0x3fb8aa3b, v16
	v_add_f32_e32 v15, v222, v15
	v_exp_f32_e32 v236, v16
	v_sub_f32_e32 v16, v41, v10
	v_add_f32_e32 v15, v223, v15
	v_mul_f32_e32 v16, 0x3fb8aa3b, v16
	v_add_f32_e32 v15, v224, v15
	v_exp_f32_e32 v41, v16
	v_sub_f32_e32 v16, v39, v10
	v_add_f32_e32 v15, v225, v15
	v_mul_f32_e32 v16, 0x3fb8aa3b, v16
	v_add_f32_e32 v15, v48, v15
	v_exp_f32_e32 v39, v16
	v_sub_f32_e32 v16, v38, v10
	v_add_f32_e32 v15, v226, v15
	v_mul_f32_e32 v16, 0x3fb8aa3b, v16
	v_add_f32_e32 v15, v227, v15
	v_exp_f32_e32 v237, v16
	v_sub_f32_e32 v16, v36, v10
	v_add_f32_e32 v15, v49, v15
	v_mul_f32_e32 v16, 0x3fb8aa3b, v16
	v_add_f32_e32 v15, v228, v15
	v_exp_f32_e32 v36, v16
	v_sub_f32_e32 v16, v34, v10
	v_add_f32_e32 v15, v229, v15
	v_mul_f32_e32 v16, 0x3fb8aa3b, v16
	v_add_f32_e32 v15, v230, v15
	v_exp_f32_e32 v34, v16
	v_sub_f32_e32 v16, v33, v10
	v_add_f32_e32 v15, v231, v15
	v_mul_f32_e32 v16, 0x3fb8aa3b, v16
	v_add_f32_e32 v15, v232, v15
	v_exp_f32_e32 v33, v16
	v_sub_f32_e32 v16, v31, v10
	v_add_f32_e32 v15, v233, v15
	v_mul_f32_e32 v16, 0x3fb8aa3b, v16
	v_add_f32_e32 v15, v234, v15
	v_exp_f32_e32 v31, v16
	v_sub_f32_e32 v16, v30, v10
	v_add_f32_e32 v15, v235, v15
	v_mul_f32_e32 v16, 0x3fb8aa3b, v16
	v_add_f32_e32 v15, v236, v15
	v_exp_f32_e32 v30, v16
	v_sub_f32_e32 v16, v21, v10
	v_add_f32_e32 v15, v41, v15
	v_mul_f32_e32 v16, 0x3fb8aa3b, v16
	v_add_f32_e32 v15, v39, v15
	v_exp_f32_e32 v238, v16
	v_sub_f32_e32 v16, v20, v10
	v_add_f32_e32 v15, v237, v15
	v_mul_f32_e32 v16, 0x3fb8aa3b, v16
	v_add_f32_e32 v15, v36, v15
	v_exp_f32_e32 v239, v16
	v_sub_f32_e32 v16, v19, v10
	v_add_f32_e32 v15, v34, v15
	v_mul_f32_e32 v16, 0x3fb8aa3b, v16
	v_add_f32_e32 v15, v33, v15
	v_exp_f32_e32 v240, v16
	v_sub_f32_e32 v16, v18, v10
	v_add_f32_e32 v15, v31, v15
	v_mul_f32_e32 v16, 0x3fb8aa3b, v16
	v_sub_f32_e32 v14, v14, v10
	v_add_f32_e32 v15, v30, v15
	v_exp_f32_e32 v241, v16
	v_mul_f32_e32 v14, 0x3fb8aa3b, v14
	v_sub_f32_e32 v12, v12, v10
	v_add_f32_e32 v15, v238, v15
	v_exp_f32_e32 v242, v14
	v_mul_f32_e32 v12, 0x3fb8aa3b, v12
	v_sub_f32_e32 v13, v13, v10
	v_add_f32_e32 v15, v239, v15
	v_exp_f32_e32 v243, v12
	v_mul_f32_e32 v13, 0x3fb8aa3b, v13
	v_sub_f32_e32 v11, v11, v10
	v_add_f32_e32 v15, v240, v15
	v_exp_f32_e32 v244, v13
	v_mul_f32_e32 v11, 0x3fb8aa3b, v11
	v_add_f32_e32 v15, v241, v15
	v_exp_f32_e32 v245, v11
	v_add_f32_e32 v14, v242, v15
	v_add_f32_e32 v12, v243, v14
	v_sub_f32_e32 v10, v211, v10
	v_add_f32_e32 v12, v244, v12
	v_mul_f32_e32 v10, 0x3fb8aa3b, v10
	v_add_f32_e32 v70, v245, v12
	v_exp_f32_e32 v72, v10
	ds_read_b64_tr_b16 v[10:11], v246 offset:32768
	ds_read_b64_tr_b16 v[12:13], v247 offset:32768
	v_cvt_pk_bf16_f32 v18, v2, v3
	v_cvt_pk_bf16_f32 v19, v4, v5
	v_cvt_pk_bf16_f32 v20, v6, v7
	v_cvt_pk_bf16_f32 v21, v8, v9
	ds_read_b64_tr_b16 v[42:43], v246 offset:33024
	ds_read_b64_tr_b16 v[44:45], v247 offset:33024
	s_waitcnt lgkmcnt(2)
	v_mfma_f32_32x32x16_bf16 v[2:17], v[10:13], v[18:21], 0
	v_cvt_pk_bf16_f32 v66, v22, v23
	v_cvt_pk_bf16_f32 v67, v24, v25
	v_cvt_pk_bf16_f32 v68, v26, v27
	v_cvt_pk_bf16_f32 v69, v28, v29
	v_add3_u32 v153, s18, v199, v200
	v_add3_u32 v151, s18, v201, v200
	ds_read_b64_tr_b16 v[22:23], v153 offset:32768
	ds_read_b64_tr_b16 v[24:25], v151 offset:32768
	s_waitcnt lgkmcnt(2)
	v_mfma_f32_32x32x16_bf16 v[2:17], v[42:45], v[66:69], v[2:17]
	v_cvt_pk_bf16_f32 v62, v32, v35
	v_cvt_pk_bf16_f32 v63, v37, v40
	v_cvt_pk_bf16_f32 v64, v75, v79
	v_cvt_pk_bf16_f32 v65, v80, v81
	v_cvt_pk_bf16_f32 v58, v146, v147
	v_cvt_pk_bf16_f32 v59, v148, v149
	v_cvt_pk_bf16_f32 v60, v150, v73
	s_waitcnt lgkmcnt(0)
	v_mfma_f32_32x32x16_bf16 v[2:17], v[22:25], v[62:65], v[2:17]
	ds_read_b64_tr_b16 v[22:23], v153 offset:33024
	ds_read_b64_tr_b16 v[24:25], v151 offset:33024
	v_cvt_pk_bf16_f32 v61, v76, v77
	s_add_i32 s18, s52, 0
	v_add3_u32 v78, s18, v199, v200
	v_add3_u32 v77, s18, v201, v200
	v_cvt_pk_bf16_f32 v54, v152, v74
	v_cvt_pk_bf16_f32 v55, v154, v155
	s_waitcnt lgkmcnt(0)
	v_mfma_f32_32x32x16_bf16 v[2:17], v[22:25], v[58:61], v[2:17]
	ds_read_b64_tr_b16 v[22:23], v78 offset:32768
	ds_read_b64_tr_b16 v[24:25], v77 offset:32768
	v_cvt_pk_bf16_f32 v56, v156, v56
	v_cvt_pk_bf16_f32 v57, v157, v175
	v_cvt_pk_bf16_f32 v50, v215, v216
	v_cvt_pk_bf16_f32 v51, v217, v218
	v_cvt_pk_bf16_f32 v52, v219, v220
	v_cvt_pk_bf16_f32 v53, v221, v222
	s_waitcnt lgkmcnt(0)
	v_mfma_f32_32x32x16_bf16 v[2:17], v[22:25], v[54:57], v[2:17]
	ds_read_b64_tr_b16 v[22:23], v78 offset:33024
	ds_read_b64_tr_b16 v[24:25], v77 offset:33024
	s_add_i32 s18, s53, 0
	v_add3_u32 v76, s18, v199, v200
	v_add3_u32 v75, s18, v201, v200
	v_cvt_pk_bf16_f32 v46, v223, v224
	v_cvt_pk_bf16_f32 v47, v225, v48
	v_cvt_pk_bf16_f32 v48, v226, v227
	s_waitcnt lgkmcnt(0)
	v_mfma_f32_32x32x16_bf16 v[2:17], v[22:25], v[50:53], v[2:17]
	ds_read_b64_tr_b16 v[22:23], v76 offset:32768
	ds_read_b64_tr_b16 v[24:25], v75 offset:32768
	v_cvt_pk_bf16_f32 v49, v49, v228
	v_cvt_pk_bf16_f32 v42, v229, v230
	v_cvt_pk_bf16_f32 v43, v231, v232
	v_cvt_pk_bf16_f32 v44, v233, v234
	v_cvt_pk_bf16_f32 v45, v235, v236
	s_add_i32 s18, s56, 0
	s_waitcnt lgkmcnt(0)
	v_mfma_f32_32x32x16_bf16 v[2:17], v[22:25], v[46:49], v[2:17]
	ds_read_b64_tr_b16 v[22:23], v76 offset:33024
	ds_read_b64_tr_b16 v[24:25], v75 offset:33024
	v_add3_u32 v74, s18, v199, v200
	v_add3_u32 v73, s18, v201, v200
	v_cvt_pk_bf16_f32 v38, v41, v39
	v_cvt_pk_bf16_f32 v39, v237, v36
	v_cvt_pk_bf16_f32 v40, v34, v33
	v_cvt_pk_bf16_f32 v41, v31, v30
	s_waitcnt lgkmcnt(0)
	v_mfma_f32_32x32x16_bf16 v[2:17], v[22:25], v[42:45], v[2:17]
	ds_read_b64_tr_b16 v[22:23], v74 offset:32768
	ds_read_b64_tr_b16 v[24:25], v73 offset:32768
	v_cvt_pk_bf16_f32 v34, v238, v239
	v_cvt_pk_bf16_f32 v35, v240, v241
	v_cvt_pk_bf16_f32 v36, v242, v243
	v_cvt_pk_bf16_f32 v37, v244, v245
	ds_bpermute_b32 v71, v212, v70
	s_cmp_lg_u32 s0, 4
	s_waitcnt lgkmcnt(1)
	v_mfma_f32_32x32x16_bf16 v[2:17], v[22:25], v[38:41], v[2:17]
	ds_read_b64_tr_b16 v[22:23], v74 offset:33024
	ds_read_b64_tr_b16 v[24:25], v73 offset:33024
	v_readlane_b32 s65, v249, 44
	s_waitcnt lgkmcnt(0)
	v_mfma_f32_32x32x16_bf16 v[2:17], v[22:25], v[34:37], v[2:17]
	ds_read_b64_tr_b16 v[22:23], v246 offset:34816
	ds_read_b64_tr_b16 v[24:25], v247 offset:34816
	ds_read_b64_tr_b16 v[146:147], v246 offset:35072
	ds_read_b64_tr_b16 v[148:149], v247 offset:35072
	s_waitcnt lgkmcnt(2)
	v_mfma_f32_32x32x16_bf16 v[18:33], v[22:25], v[18:21], 0
	s_waitcnt lgkmcnt(0)
	v_mfma_f32_32x32x16_bf16 v[18:33], v[146:149], v[66:69], v[18:33]
	ds_read_b64_tr_b16 v[66:67], v153 offset:34816
	ds_read_b64_tr_b16 v[68:69], v151 offset:34816
	s_waitcnt lgkmcnt(0)
	v_mfma_f32_32x32x16_bf16 v[18:33], v[66:69], v[62:65], v[18:33]
	ds_read_b64_tr_b16 v[62:63], v153 offset:35072
	ds_read_b64_tr_b16 v[64:65], v151 offset:35072
	s_waitcnt lgkmcnt(0)
	v_mfma_f32_32x32x16_bf16 v[18:33], v[62:65], v[58:61], v[18:33]
	ds_read_b64_tr_b16 v[58:59], v78 offset:34816
	ds_read_b64_tr_b16 v[60:61], v77 offset:34816
	s_waitcnt lgkmcnt(0)
	v_mfma_f32_32x32x16_bf16 v[18:33], v[58:61], v[54:57], v[18:33]
	ds_read_b64_tr_b16 v[54:55], v78 offset:35072
	ds_read_b64_tr_b16 v[56:57], v77 offset:35072
	s_waitcnt lgkmcnt(0)
	v_mfma_f32_32x32x16_bf16 v[18:33], v[54:57], v[50:53], v[18:33]
	ds_read_b64_tr_b16 v[50:51], v76 offset:34816
	ds_read_b64_tr_b16 v[52:53], v75 offset:34816
	s_waitcnt lgkmcnt(0)
	v_mfma_f32_32x32x16_bf16 v[18:33], v[50:53], v[46:49], v[18:33]
	ds_read_b64_tr_b16 v[46:47], v76 offset:35072
	ds_read_b64_tr_b16 v[48:49], v75 offset:35072
	s_waitcnt lgkmcnt(0)
	v_mfma_f32_32x32x16_bf16 v[18:33], v[46:49], v[42:45], v[18:33]
	ds_read_b64_tr_b16 v[42:43], v74 offset:34816
	ds_read_b64_tr_b16 v[44:45], v73 offset:34816
	s_waitcnt lgkmcnt(0)
	v_mfma_f32_32x32x16_bf16 v[18:33], v[42:45], v[38:41], v[18:33]
	ds_read_b64_tr_b16 v[38:39], v74 offset:35072
	ds_read_b64_tr_b16 v[40:41], v73 offset:35072
	s_waitcnt lgkmcnt(0)
	v_mfma_f32_32x32x16_bf16 v[18:33], v[38:41], v[34:37], v[18:33]
	v_add_f32_e32 v34, v70, v71
	v_add_f32_e32 v34, v72, v34
	v_rcp_f32_e32 v34, v34
	s_waitcnt vmcnt(3)
	v_lshlrev_b32_e32 v36, 16, v196
	v_and_b32_e32 v37, 0xffff0000, v196
	v_pk_mul_f32 v[2:3], v[2:3], v[34:35] op_sel_hi:[1,0]
	s_nop 0
	v_pk_mul_f32 v[2:3], v[2:3], v[36:37]
	v_pk_mul_f32 v[4:5], v[4:5], v[34:35] op_sel_hi:[1,0]
	v_lshlrev_b32_e32 v36, 16, v197
	v_and_b32_e32 v37, 0xffff0000, v197
	v_pk_mul_f32 v[4:5], v[4:5], v[36:37]
	v_cvt_pk_bf16_f32 v2, v2, v3
	v_cvt_pk_bf16_f32 v3, v4, v5
	v_mad_u64_u32 v[4:5], s[18:19], v213, s48, v[180:181]
	v_mov_b32_e32 v36, v5
	v_mad_u64_u32 v[36:37], s[18:19], v214, s48, v[36:37]
	v_mov_b32_e32 v5, v36
	global_store_dwordx2 v[4:5], v[2:3], off
	v_pk_mul_f32 v[2:3], v[6:7], v[34:35] op_sel_hi:[1,0]
	v_lshlrev_b32_e32 v6, 16, v194
	v_and_b32_e32 v7, 0xffff0000, v194
	v_pk_mul_f32 v[2:3], v[2:3], v[6:7]
	v_pk_mul_f32 v[6:7], v[8:9], v[34:35] op_sel_hi:[1,0]
	v_lshlrev_b32_e32 v8, 16, v195
	v_and_b32_e32 v9, 0xffff0000, v195
	v_pk_mul_f32 v[6:7], v[6:7], v[8:9]
	v_cvt_pk_bf16_f32 v2, v2, v3
	v_cvt_pk_bf16_f32 v3, v6, v7
	global_store_dwordx2 v[4:5], v[2:3], off offset:16
	v_pk_mul_f32 v[2:3], v[10:11], v[34:35] op_sel_hi:[1,0]
	v_lshlrev_b32_e32 v6, 16, v192
	v_and_b32_e32 v7, 0xffff0000, v192
	v_pk_mul_f32 v[2:3], v[2:3], v[6:7]
	v_pk_mul_f32 v[6:7], v[12:13], v[34:35] op_sel_hi:[1,0]
	v_lshlrev_b32_e32 v8, 16, v193
	v_and_b32_e32 v9, 0xffff0000, v193
	v_pk_mul_f32 v[6:7], v[6:7], v[8:9]
	v_cvt_pk_bf16_f32 v2, v2, v3
	v_cvt_pk_bf16_f32 v3, v6, v7
	global_store_dwordx2 v[4:5], v[2:3], off offset:32
	v_pk_mul_f32 v[2:3], v[14:15], v[34:35] op_sel_hi:[1,0]
	v_lshlrev_b32_e32 v6, 16, v190
	v_and_b32_e32 v7, 0xffff0000, v190
	v_pk_mul_f32 v[2:3], v[2:3], v[6:7]
	v_pk_mul_f32 v[6:7], v[16:17], v[34:35] op_sel_hi:[1,0]
	v_lshlrev_b32_e32 v8, 16, v191
	v_and_b32_e32 v9, 0xffff0000, v191
	v_pk_mul_f32 v[6:7], v[6:7], v[8:9]
	v_cvt_pk_bf16_f32 v2, v2, v3
	v_cvt_pk_bf16_f32 v3, v6, v7
	global_store_dwordx2 v[4:5], v[2:3], off offset:48
	v_pk_mul_f32 v[2:3], v[18:19], v[34:35] op_sel_hi:[1,0]
	v_lshlrev_b32_e32 v6, 16, v188
	v_and_b32_e32 v7, 0xffff0000, v188
	v_pk_mul_f32 v[2:3], v[2:3], v[6:7]
	v_pk_mul_f32 v[6:7], v[20:21], v[34:35] op_sel_hi:[1,0]
	v_lshlrev_b32_e32 v8, 16, v189
	v_and_b32_e32 v9, 0xffff0000, v189
	v_pk_mul_f32 v[6:7], v[6:7], v[8:9]
	v_cvt_pk_bf16_f32 v2, v2, v3
	v_cvt_pk_bf16_f32 v3, v6, v7
	global_store_dwordx2 v[4:5], v[2:3], off offset:64
	v_pk_mul_f32 v[2:3], v[22:23], v[34:35] op_sel_hi:[1,0]
	s_waitcnt vmcnt(7)
	v_lshlrev_b32_e32 v6, 16, v186
	v_and_b32_e32 v7, 0xffff0000, v186
	v_pk_mul_f32 v[2:3], v[2:3], v[6:7]
	v_pk_mul_f32 v[6:7], v[24:25], v[34:35] op_sel_hi:[1,0]
	v_lshlrev_b32_e32 v8, 16, v187
	v_and_b32_e32 v9, 0xffff0000, v187
	v_pk_mul_f32 v[6:7], v[6:7], v[8:9]
	v_cvt_pk_bf16_f32 v2, v2, v3
	v_cvt_pk_bf16_f32 v3, v6, v7
	global_store_dwordx2 v[4:5], v[2:3], off offset:80
	v_pk_mul_f32 v[2:3], v[26:27], v[34:35] op_sel_hi:[1,0]
	s_waitcnt vmcnt(7)
	v_lshlrev_b32_e32 v6, 16, v184
	v_and_b32_e32 v7, 0xffff0000, v184
	v_pk_mul_f32 v[2:3], v[2:3], v[6:7]
	v_pk_mul_f32 v[6:7], v[28:29], v[34:35] op_sel_hi:[1,0]
	v_lshlrev_b32_e32 v8, 16, v185
	v_and_b32_e32 v9, 0xffff0000, v185
	v_pk_mul_f32 v[6:7], v[6:7], v[8:9]
	v_cvt_pk_bf16_f32 v2, v2, v3
	v_cvt_pk_bf16_f32 v3, v6, v7
	global_store_dwordx2 v[4:5], v[2:3], off offset:96
	v_pk_mul_f32 v[2:3], v[30:31], v[34:35] op_sel_hi:[1,0]
	s_waitcnt vmcnt(7)
	v_lshlrev_b32_e32 v6, 16, v182
	v_and_b32_e32 v7, 0xffff0000, v182
	v_pk_mul_f32 v[2:3], v[2:3], v[6:7]
	v_pk_mul_f32 v[6:7], v[32:33], v[34:35] op_sel_hi:[1,0]
	v_lshlrev_b32_e32 v8, 16, v183
	v_and_b32_e32 v9, 0xffff0000, v183
	v_pk_mul_f32 v[6:7], v[6:7], v[8:9]
	v_cvt_pk_bf16_f32 v2, v2, v3
	v_cvt_pk_bf16_f32 v3, v6, v7
	global_store_dwordx2 v[4:5], v[2:3], off offset:112
	v_mov_b64_e32 v[10:11], v[142:143]
	v_mov_b64_e32 v[2:3], v[138:139]
	v_mov_b64_e32 v[14:15], v[134:135]
	v_mov_b64_e32 v[6:7], v[130:131]
	v_mov_b64_e32 v[12:13], v[144:145]
	v_mov_b64_e32 v[4:5], v[140:141]
	v_mov_b64_e32 v[16:17], v[136:137]
	v_mov_b64_e32 v[8:9], v[132:133]
	s_cbranch_scc0 .LBB0_757
